# adds removal of NaN-canonicalising self-max instructions in attention softmax max trees (with MFMA distance re-padded) on top of peel + saddr loads
# speedup vs baseline: 1.0144x; 1.0033x over previous
.LBB0_430:
	s_not_b32 s8, s0
	s_add_i32 s12, s68, s8
	s_and_b64 s[8:9], s[10:11], exec
	s_cselect_b32 s8, s0, s12
	s_waitcnt lgkmcnt(0)
	s_barrier
	s_lshl_b32 s8, s8, 6
	s_add_i32 s8, s8, s69
	s_and_b64 vcc, exec, s[54:55]
	s_cbranch_vccz .LBB0_445
	v_or_b32_e32 v2, s8, v170
	v_ashrrev_i32_e32 v3, 31, v2
	v_lshlrev_b64 v[4:5], 11, v[2:3]
	s_lshl_b64 s[12:13], s[38:39], 1
	v_or_b32_e32 v5, s13, v5
	v_or_b32_e32 v4, s12, v4
	v_lshl_add_u64 v[12:13], s[30:31], 0, v[4:5]
	v_lshl_add_u64 v[84:85], s[42:43], 0, v[4:5]
	v_mov_b64_e32 v[4:5], s[74:75]
	v_mad_i64_i32 v[2:3], s[12:13], v2, s85, v[4:5]
	s_lshl_b32 s46, s83, 1
	v_lshl_add_u64 v[2:3], v[2:3], 0, s[46:47]
	s_lshl_b32 s46, s29, 1
	v_lshl_add_u64 v[86:87], v[2:3], 0, s[46:47]
	global_load_dwordx4 v[104:107], v[12:13], off offset:16
	global_load_dwordx4 v[8:11], v[12:13], off
	global_load_dwordx4 v[100:103], v[84:85], off offset:16
	global_load_dwordx4 v[80:83], v[84:85], off
	global_load_dwordx4 v[88:91], v[12:13], off offset:144
	global_load_dwordx4 v[96:99], v[12:13], off offset:128
	global_load_dwordx4 v[2:5], v[84:85], off offset:144
	global_load_dwordx4 v[92:95], v[84:85], off offset:128
	v_or_b32_e32 v12, s8, v206
	v_ashrrev_i32_e32 v13, 31, v12
	v_lshlrev_b64 v[12:13], 5, v[12:13]
	v_lshl_add_u64 v[84:85], s[56:57], 0, v[12:13]
	v_lshl_add_u64 v[12:13], s[2:3], 0, v[12:13]
	global_load_dword v0, v[84:85], off
	global_load_dword v108, v[12:13], off
	v_add_u32_e32 v12, s1, v209
	v_lshl_add_u64 v[6:7], v[86:87], 0, s[40:41]
	v_add_u32_e32 v109, s18, v209
	s_waitcnt vmcnt(0)
	ds_write2_b64 v12, v[8:9], v[10:11] offset1:1
	v_add_u32_e32 v8, 0x4200, v12
	ds_write2_b64 v8, v[80:81], v[82:83] offset1:1
	v_add_u32_e32 v8, s88, v210
	ds_write_b16 v8, v80 offset:33792
	v_add_u32_e32 v8, s27, v210
	ds_write_b16_d16_hi v8, v80 offset:33792
	ds_write_b16 v8, v81 offset:33936
	ds_write_b16_d16_hi v8, v81 offset:34080
	ds_write_b16 v8, v82 offset:34224
	ds_write_b16_d16_hi v8, v82 offset:34368
	ds_write_b16 v8, v83 offset:34512
	ds_write_b16_d16_hi v8, v83 offset:34656
	v_add_co_u32_e32 v8, vcc, s33, v86
	s_nop 1
	v_addc_co_u32_e32 v9, vcc, 0, v87, vcc
	global_load_dwordx4 v[84:87], v[8:9], off
	global_load_dwordx4 v[80:83], v[6:7], off offset:16
	global_load_dwordx4 v[10:13], v[6:7], off offset:128
	s_nop 0
	global_load_dwordx4 v[6:9], v[6:7], off offset:144
	ds_write2_b64 v109, v[104:105], v[106:107] offset1:1
	v_add_u32_e32 v104, 0x4200, v109
	ds_write2_b64 v104, v[100:101], v[102:103] offset1:1
	v_add_u32_e32 v104, s19, v210
	v_add_u32_e32 v105, s64, v210
	ds_write_b16 v104, v100 offset:33792
	ds_write_b16_d16_hi v105, v100 offset:33792
	ds_write_b16 v105, v101 offset:33936
	ds_write_b16_d16_hi v105, v101 offset:34080
	ds_write_b16 v105, v102 offset:34224
	ds_write_b16_d16_hi v105, v102 offset:34368
	ds_write_b16 v105, v103 offset:34512
	ds_write_b16_d16_hi v105, v103 offset:34656
	v_add_u32_e32 v100, s90, v209
	ds_write2_b64 v100, v[96:97], v[98:99] offset1:1
	v_add_u32_e32 v96, 0x4200, v100
	ds_write2_b64 v96, v[92:93], v[94:95] offset1:1
	ds_write_b16 v104, v92 offset:41856
	v_add_u32_e32 v96, s91, v210
	ds_write_b16_d16_hi v96, v92 offset:33792
	ds_write_b16 v96, v93 offset:33936
	ds_write_b16_d16_hi v96, v93 offset:34080
	ds_write_b16 v96, v94 offset:34224
	ds_write_b16_d16_hi v96, v94 offset:34368
	ds_write_b16 v96, v95 offset:34512
	ds_write_b16_d16_hi v96, v95 offset:34656
	v_add_u32_e32 v92, s67, v209
	ds_write2_b64 v92, v[88:89], v[90:91] offset1:1
	v_add_u32_e32 v88, 0x4200, v92
	ds_write2_b64 v88, v[2:3], v[4:5] offset1:1
	ds_write_b16 v104, v2 offset:43008
	v_add_u32_e32 v88, s24, v210
	ds_write_b16_d16_hi v88, v2 offset:33792
	ds_write_b16 v88, v3 offset:33936
	ds_write_b16_d16_hi v88, v3 offset:34080
	ds_write_b16 v88, v4 offset:34224
	ds_write_b16_d16_hi v88, v4 offset:34368
	ds_write_b16 v88, v5 offset:34512
	ds_write_b16_d16_hi v88, v5 offset:34656
	v_add_f32_dpp v2, v108, v108 row_shr:1 row_mask:0xf bank_mask:0xf bound_ctrl:1
	v_mov_b32_e32 v3, v1
	v_mov_b32_e32 v4, 0xff61b1e6
	v_add_f32_dpp v2, v2, v2 row_shr:2 row_mask:0xf bank_mask:0xf bound_ctrl:1
	s_nop 1
	v_add_f32_dpp v2, v2, v2 row_shr:4 row_mask:0xf bank_mask:0xf bound_ctrl:1
	s_nop 1
	v_add_f32_dpp v2, v2, v2 row_shr:8 row_mask:0xf bank_mask:0xf bound_ctrl:1
	s_nop 1
	v_mov_b32_dpp v3, v2 row_bcast:15 row_mask:0xa bank_mask:0xf
	v_add_f32_e32 v2, v2, v3
	v_mov_b32_e32 v3, v1
	s_nop 1
	v_mov_b32_dpp v3, v2 row_bcast:31 row_mask:0xc bank_mask:0xf
	v_add_f32_e32 v2, v2, v3
	v_sub_f32_e32 v0, v0, v2
	v_mov_b32_e32 v3, 0xff61b1e6
	s_nop 1
	v_mov_b32_dpp v3, v0 row_shr:1 row_mask:0xf bank_mask:0xf
	v_max_f32_e32 v3, v0, v3
	s_nop 1
	v_mov_b32_dpp v4, v3 row_shr:2 row_mask:0xf bank_mask:0xf
	v_max_f32_e32 v3, v3, v4
	v_mov_b32_e32 v4, 0xff61b1e6
	s_nop 1
	v_mov_b32_dpp v4, v3 row_shr:4 row_mask:0xf bank_mask:0xf
	v_max_f32_e32 v3, v3, v4
	v_mov_b32_e32 v4, 0xff61b1e6
	s_nop 1
	v_mov_b32_dpp v4, v3 row_shr:8 row_mask:0xf bank_mask:0xf
	v_max_f32_e32 v3, v3, v4
	v_mov_b32_e32 v4, 0xff61b1e6
	s_nop 1
	v_mov_b32_dpp v4, v3 row_bcast:15 row_mask:0xa bank_mask:0xf
	v_max_f32_e32 v3, v3, v4
	v_mov_b32_e32 v4, 0xff61b1e6
	s_nop 1
	v_mov_b32_dpp v4, v3 row_bcast:31 row_mask:0xc bank_mask:0xf
	v_max3_f32 v3, v217, v3, v4
	s_nop 0
	v_readlane_b32 s9, v3, 63
	s_nop 1
	v_subrev_f32_e32 v4, s9, v0
	v_mul_f32_e32 v4, 0x3fb8aa3b, v4
	v_exp_f32_e32 v4, v4
	ds_write2st64_b32 v211, v0, v3 offset1:1
	ds_write2st64_b32 v211, v2, v4 offset0:2 offset1:3
	v_add_u32_e32 v0, s17, v210
	s_waitcnt vmcnt(3)
	ds_write_b16 v0, v84 offset:52224
	v_add_u32_e32 v0, s78, v210
	ds_write_b16_d16_hi v0, v84 offset:52224
	ds_write_b16 v0, v85 offset:52360
	ds_write_b16_d16_hi v0, v85 offset:52496
	ds_write_b16 v0, v86 offset:52632
	ds_write_b16_d16_hi v0, v86 offset:52768
	ds_write_b16 v0, v87 offset:52904
	ds_write_b16_d16_hi v0, v87 offset:53040
	v_add_u32_e32 v0, s79, v210
	v_add_u32_e32 v2, s65, v210
	s_waitcnt vmcnt(2)
	ds_write_b16 v0, v80 offset:52224
	ds_write_b16_d16_hi v2, v80 offset:52224
	ds_write_b16 v2, v81 offset:52360
	ds_write_b16_d16_hi v2, v81 offset:52496
	ds_write_b16 v2, v82 offset:52632
	ds_write_b16_d16_hi v2, v82 offset:52768
	ds_write_b16 v2, v83 offset:52904
	ds_write_b16_d16_hi v2, v83 offset:53040
	s_waitcnt vmcnt(1)
	ds_write_b16 v0, v10 offset:59840
	v_add_u32_e32 v2, s66, v210
	ds_write_b16_d16_hi v2, v10 offset:52224
	ds_write_b16 v2, v11 offset:52360
	ds_write_b16_d16_hi v2, v11 offset:52496
	ds_write_b16 v2, v12 offset:52632
	ds_write_b16_d16_hi v2, v12 offset:52768
	ds_write_b16 v2, v13 offset:52904
	ds_write_b16_d16_hi v2, v13 offset:53040
	s_waitcnt vmcnt(0)
	ds_write_b16 v0, v6 offset:60928
	v_add_u32_e32 v0, s25, v210
	ds_write_b16_d16_hi v0, v6 offset:52224
	ds_write_b16 v0, v7 offset:52360
	ds_write_b16_d16_hi v0, v7 offset:52496
	ds_write_b16 v0, v8 offset:52632
	ds_write_b16_d16_hi v0, v8 offset:52768
	ds_write_b16 v0, v9 offset:52904
	ds_write_b16_d16_hi v0, v9 offset:53040
	s_waitcnt lgkmcnt(0)
	s_barrier
	s_mov_b64 s[12:13], -1
	s_cbranch_execz .LBB0_446
	s_mov_b32 s46, s28
	s_and_b64 vcc, exec, s[12:13]
	s_cbranch_vccz .LBB0_455

.LBB0_453:
	v_add_f32_dpp v3, v207, v207 row_shr:1 row_mask:0xf bank_mask:0xf bound_ctrl:1
	v_mov_b32_e32 v4, v1
	v_mov_b32_e32 v5, 0xff61b1e6
	v_add_f32_dpp v3, v3, v3 row_shr:2 row_mask:0xf bank_mask:0xf bound_ctrl:1
	v_mov_b32_e32 v6, 0xff61b1e6
	s_bitcmp1_b32 s0, 0
	v_add_f32_dpp v3, v3, v3 row_shr:4 row_mask:0xf bank_mask:0xf bound_ctrl:1
	s_waitcnt vmcnt(0)
	v_mov_b32_e32 v207, v0
	v_add_f32_dpp v3, v3, v3 row_shr:8 row_mask:0xf bank_mask:0xf bound_ctrl:1
	s_nop 1
	v_mov_b32_dpp v4, v3 row_bcast:15 row_mask:0xa bank_mask:0xf
	v_add_f32_e32 v3, v3, v4
	v_mov_b32_e32 v4, v1
	s_nop 1
	v_mov_b32_dpp v4, v3 row_bcast:31 row_mask:0xc bank_mask:0xf
	v_add_f32_e32 v3, v3, v4
	v_sub_f32_e32 v4, v208, v3
	v_mov_b32_e32 v208, v2
	s_nop 0
	v_mov_b32_dpp v5, v4 row_shr:1 row_mask:0xf bank_mask:0xf
	v_max_f32_e32 v5, v4, v5
	s_nop 1
	v_mov_b32_dpp v6, v5 row_shr:2 row_mask:0xf bank_mask:0xf
	v_max_f32_e32 v5, v5, v6
	v_mov_b32_e32 v6, 0xff61b1e6
	s_nop 1
	v_mov_b32_dpp v6, v5 row_shr:4 row_mask:0xf bank_mask:0xf
	v_max_f32_e32 v5, v5, v6
	v_mov_b32_e32 v6, 0xff61b1e6
	s_nop 1
	v_mov_b32_dpp v6, v5 row_shr:8 row_mask:0xf bank_mask:0xf
	v_max_f32_e32 v5, v5, v6
	v_mov_b32_e32 v6, 0xff61b1e6
	s_nop 1
	v_mov_b32_dpp v6, v5 row_bcast:15 row_mask:0xa bank_mask:0xf
	v_max_f32_e32 v5, v5, v6
	v_mov_b32_e32 v6, 0xff61b1e6
	s_nop 1
	v_mov_b32_dpp v6, v5 row_bcast:31 row_mask:0xc bank_mask:0xf
	v_max3_f32 v5, v217, v5, v6
	s_nop 0
	v_readlane_b32 s12, v5, 63
	s_nop 1
	v_subrev_f32_e32 v6, s12, v4
	v_mul_f32_e32 v6, 0x3fb8aa3b, v6
	v_exp_f32_e32 v6, v6
	s_cselect_b32 s12, 0x11000, 0
	s_add_i32 s46, s12, 0
	ds_write2st64_b32 v211, v4, v5 offset1:1
	ds_write2st64_b32 v211, v3, v6 offset0:2 offset1:3
	s_mov_b64 s[12:13], s[60:61]
	s_and_b64 vcc, exec, s[12:13]
	s_cbranch_vccz .LBB0_455
	s_branch .LBB0_433

.LBB0_487:
	s_and_b32 s13, s14, 1
	s_mul_i32 s15, s13, 0xa800
	s_add_i32 s15, s15, 0
	v_add3_u32 v0, s15, v248, v171
	ds_read_b128 v[66:69], v0
	ds_read_b128 v[146:149], v0 offset:32
	s_waitcnt lgkmcnt(1)
	v_mfma_f32_32x32x16_bf16 v[82:97], v[66:69], v[126:129], 0
	ds_read_b128 v[66:69], v0 offset:12800
	ds_read_b128 v[150:153], v0 offset:12832
	s_waitcnt lgkmcnt(1)
	v_mfma_f32_32x32x16_bf16 v[66:81], v[66:69], v[126:129], 0
	v_mfma_f32_32x32x16_bf16 v[82:97], v[146:149], v[122:125], v[82:97]
	s_waitcnt lgkmcnt(0)
	v_mfma_f32_32x32x16_bf16 v[66:81], v[150:153], v[122:125], v[66:81]
	ds_read_b128 v[146:149], v0 offset:64
	ds_read_b128 v[150:153], v0 offset:96
	s_waitcnt lgkmcnt(1)
	v_mfma_f32_32x32x16_bf16 v[82:97], v[146:149], v[118:121], v[82:97]
	ds_read_b128 v[146:149], v0 offset:12864
	ds_read_b128 v[154:157], v0 offset:12896
	s_waitcnt lgkmcnt(1)
	v_mfma_f32_32x32x16_bf16 v[66:81], v[146:149], v[118:121], v[66:81]
	v_mfma_f32_32x32x16_bf16 v[82:97], v[150:153], v[114:117], v[82:97]
	ds_read_b128 v[146:149], v0 offset:128
	ds_read_b128 v[150:153], v0 offset:160
	s_waitcnt lgkmcnt(2)
	v_mfma_f32_32x32x16_bf16 v[66:81], v[154:157], v[114:117], v[66:81]
	s_waitcnt lgkmcnt(1)
	v_mfma_f32_32x32x16_bf16 v[82:97], v[146:149], v[110:113], v[82:97]
	ds_read_b128 v[146:149], v0 offset:12928
	ds_read_b128 v[154:157], v0 offset:12960
	s_waitcnt lgkmcnt(1)
	v_mfma_f32_32x32x16_bf16 v[66:81], v[146:149], v[110:113], v[66:81]
	v_mfma_f32_32x32x16_bf16 v[82:97], v[150:153], v[106:109], v[82:97]
	ds_read_b128 v[146:149], v0 offset:192
	ds_read_b128 v[150:153], v0 offset:224
	s_waitcnt lgkmcnt(2)
	v_mfma_f32_32x32x16_bf16 v[66:81], v[154:157], v[106:109], v[66:81]
	s_waitcnt lgkmcnt(1)
	v_mfma_f32_32x32x16_bf16 v[82:97], v[146:149], v[102:105], v[82:97]
	ds_read_b128 v[146:149], v0 offset:12992
	ds_read_b128 v[154:157], v0 offset:13024
	s_waitcnt lgkmcnt(1)
	v_mfma_f32_32x32x16_bf16 v[66:81], v[146:149], v[102:105], v[66:81]
	v_mfma_f32_32x32x16_bf16 v[82:97], v[150:153], v[98:101], v[82:97]
	ds_read_b128 v[146:149], v0 offset:256
	ds_read_b128 v[150:153], v0 offset:288
	s_waitcnt lgkmcnt(2)
	v_mfma_f32_32x32x16_bf16 v[66:81], v[154:157], v[98:101], v[66:81]
	s_waitcnt lgkmcnt(1)
	v_mfma_f32_32x32x16_bf16 v[82:97], v[146:149], v[134:137], v[82:97]
	ds_read_b128 v[146:149], v0 offset:13056
	ds_read_b128 v[154:157], v0 offset:13088
	s_waitcnt lgkmcnt(1)
	v_mfma_f32_32x32x16_bf16 v[66:81], v[146:149], v[134:137], v[66:81]
	ds_read_b128 v[146:149], v0 offset:320
	ds_read_b128 v[242:245], v0 offset:352
	v_mfma_f32_32x32x16_bf16 v[82:97], v[150:153], v[130:133], v[82:97]
	s_waitcnt lgkmcnt(2)
	v_mfma_f32_32x32x16_bf16 v[66:81], v[154:157], v[130:133], v[66:81]
	s_waitcnt lgkmcnt(1)
	v_mfma_f32_32x32x16_bf16 v[82:97], v[146:149], v[142:145], v[82:97]
	ds_read_b128 v[146:149], v0 offset:13120
	ds_read_b128 v[150:153], v0 offset:13152
	global_load_dwordx4 v[162:165], v[224:225], off
	global_load_dwordx4 v[158:161], v[226:227], off
	global_load_dwordx4 v[154:157], v[228:229], off
	v_mov_b32_e32 v0, v223
	s_waitcnt lgkmcnt(1)
	v_mfma_f32_32x32x16_bf16 v[66:81], v[146:149], v[142:145], v[66:81]
	s_waitcnt lgkmcnt(0)
	v_mfma_f32_32x32x16_bf16 v[66:81], v[150:153], v[138:141], v[66:81]
	global_load_dwordx4 v[150:153], v[230:231], off
	global_load_dwordx4 v[146:149], v[230:231], off offset:16
	v_mfma_f32_32x32x16_bf16 v[82:97], v[242:245], v[138:141], v[82:97]
	s_nop 8
	s_nop 1
	s_nop 0
	v_max_f32_e32 v217, v83, v67
	v_max_f32_e32 v222, v84, v68
	v_max3_f32 v217, v82, v66, v217
	v_max_f32_e32 v223, v85, v69
	v_max3_f32 v217, v217, v222, v223
	v_max_f32_e32 v222, v86, v70
	v_max_f32_e32 v223, v87, v71
	v_max3_f32 v217, v217, v222, v223
	v_max_f32_e32 v222, v88, v72
	v_max_f32_e32 v223, v89, v73
	v_max3_f32 v217, v217, v222, v223
	v_max_f32_e32 v222, v90, v74
	v_max_f32_e32 v223, v91, v75
	v_max3_f32 v217, v217, v222, v223
	v_max_f32_e32 v222, v92, v76
	v_max_f32_e32 v223, v93, v77
	v_max3_f32 v217, v217, v222, v223
	v_max_f32_e32 v222, v94, v78
	v_max_f32_e32 v223, v95, v79
	v_max3_f32 v217, v217, v222, v223
	v_max_f32_e32 v222, v96, v80
	v_max_f32_e32 v223, v97, v81
	v_max3_f32 v217, v217, v222, v223
	v_mov_b32_e32 v222, v217
	s_nop 1
	v_permlane32_swap_b32_e32 v217, v222
	v_max3_f32 v223, v0, v217, v222
	v_sub_f32_e32 v0, v0, v223
	v_mul_f32_e32 v0, 0x3dd53b94, v0
	v_exp_f32_e32 v232, v0
	s_nop 0
	v_cmp_eq_f32_e32 vcc, 1.0, v232
	s_cmp_eq_u64 vcc, exec
	s_cbranch_scc1 .LBB0_489
	v_pk_mul_f32 v[64:65], v[64:65], v[232:233] op_sel_hi:[1,0]
	v_pk_mul_f32 v[62:63], v[62:63], v[232:233] op_sel_hi:[1,0]
	v_pk_mul_f32 v[60:61], v[60:61], v[232:233] op_sel_hi:[1,0]
	v_pk_mul_f32 v[58:59], v[58:59], v[232:233] op_sel_hi:[1,0]
	v_pk_mul_f32 v[56:57], v[56:57], v[232:233] op_sel_hi:[1,0]
	v_pk_mul_f32 v[54:55], v[54:55], v[232:233] op_sel_hi:[1,0]
	v_pk_mul_f32 v[52:53], v[52:53], v[232:233] op_sel_hi:[1,0]
	v_pk_mul_f32 v[50:51], v[50:51], v[232:233] op_sel_hi:[1,0]
	v_pk_mul_f32 v[48:49], v[48:49], v[232:233] op_sel_hi:[1,0]
	v_pk_mul_f32 v[46:47], v[46:47], v[232:233] op_sel_hi:[1,0]
	v_pk_mul_f32 v[44:45], v[44:45], v[232:233] op_sel_hi:[1,0]
	v_pk_mul_f32 v[42:43], v[42:43], v[232:233] op_sel_hi:[1,0]
	v_pk_mul_f32 v[40:41], v[40:41], v[232:233] op_sel_hi:[1,0]
	v_pk_mul_f32 v[38:39], v[38:39], v[232:233] op_sel_hi:[1,0]
	v_pk_mul_f32 v[36:37], v[36:37], v[232:233] op_sel_hi:[1,0]
	v_pk_mul_f32 v[34:35], v[34:35], v[232:233] op_sel_hi:[1,0]
	v_pk_mul_f32 v[32:33], v[32:33], v[232:233] op_sel_hi:[1,0]
	v_pk_mul_f32 v[30:31], v[30:31], v[232:233] op_sel_hi:[1,0]
	v_pk_mul_f32 v[28:29], v[28:29], v[232:233] op_sel_hi:[1,0]
	v_pk_mul_f32 v[26:27], v[26:27], v[232:233] op_sel_hi:[1,0]
	v_pk_mul_f32 v[24:25], v[24:25], v[232:233] op_sel_hi:[1,0]
	v_pk_mul_f32 v[22:23], v[22:23], v[232:233] op_sel_hi:[1,0]
	v_pk_mul_f32 v[20:21], v[20:21], v[232:233] op_sel_hi:[1,0]
	v_pk_mul_f32 v[18:19], v[18:19], v[232:233] op_sel_hi:[1,0]
	v_pk_mul_f32 v[16:17], v[16:17], v[232:233] op_sel_hi:[1,0]
	v_pk_mul_f32 v[14:15], v[14:15], v[232:233] op_sel_hi:[1,0]
	v_pk_mul_f32 v[12:13], v[12:13], v[232:233] op_sel_hi:[1,0]
	v_pk_mul_f32 v[10:11], v[10:11], v[232:233] op_sel_hi:[1,0]
	v_pk_mul_f32 v[8:9], v[8:9], v[232:233] op_sel_hi:[1,0]
	v_pk_mul_f32 v[6:7], v[6:7], v[232:233] op_sel_hi:[1,0]
	v_pk_mul_f32 v[4:5], v[4:5], v[232:233] op_sel_hi:[1,0]
	v_pk_mul_f32 v[2:3], v[2:3], v[232:233] op_sel_hi:[1,0]

.LBB0_491:
	s_bitcmp1_b32 s12, 0
	s_cselect_b32 s12, 0xa800, 0
	s_add_i32 s12, s12, 0
	v_add3_u32 v0, s12, v248, v171
	ds_read_b128 v[66:69], v0
	s_waitcnt lgkmcnt(0)
	v_mfma_f32_32x32x16_bf16 v[82:97], v[66:69], v[126:129], 0
	ds_read_b128 v[66:69], v0 offset:12800
	s_waitcnt lgkmcnt(0)
	v_mfma_f32_32x32x16_bf16 v[66:81], v[66:69], v[126:129], 0
	ds_read_b128 v[126:129], v0 offset:32
	s_waitcnt lgkmcnt(0)
	v_mfma_f32_32x32x16_bf16 v[82:97], v[126:129], v[122:125], v[82:97]
	ds_read_b128 v[126:129], v0 offset:12832
	s_waitcnt lgkmcnt(0)
	v_mfma_f32_32x32x16_bf16 v[66:81], v[126:129], v[122:125], v[66:81]
	ds_read_b128 v[122:125], v0 offset:64
	s_waitcnt lgkmcnt(0)
	v_mfma_f32_32x32x16_bf16 v[82:97], v[122:125], v[118:121], v[82:97]
	ds_read_b128 v[122:125], v0 offset:12864
	s_waitcnt lgkmcnt(0)
	v_mfma_f32_32x32x16_bf16 v[66:81], v[122:125], v[118:121], v[66:81]
	ds_read_b128 v[118:121], v0 offset:96
	s_waitcnt lgkmcnt(0)
	v_mfma_f32_32x32x16_bf16 v[82:97], v[118:121], v[114:117], v[82:97]
	ds_read_b128 v[118:121], v0 offset:12896
	s_waitcnt lgkmcnt(0)
	v_mfma_f32_32x32x16_bf16 v[66:81], v[118:121], v[114:117], v[66:81]
	ds_read_b128 v[114:117], v0 offset:128
	s_waitcnt lgkmcnt(0)
	v_mfma_f32_32x32x16_bf16 v[82:97], v[114:117], v[110:113], v[82:97]
	ds_read_b128 v[114:117], v0 offset:12928
	s_waitcnt lgkmcnt(0)
	v_mfma_f32_32x32x16_bf16 v[66:81], v[114:117], v[110:113], v[66:81]
	ds_read_b128 v[110:113], v0 offset:160
	s_waitcnt lgkmcnt(0)
	v_mfma_f32_32x32x16_bf16 v[82:97], v[110:113], v[106:109], v[82:97]
	ds_read_b128 v[110:113], v0 offset:12960
	s_waitcnt lgkmcnt(0)
	v_mfma_f32_32x32x16_bf16 v[66:81], v[110:113], v[106:109], v[66:81]
	ds_read_b128 v[106:109], v0 offset:192
	s_waitcnt lgkmcnt(0)
	v_mfma_f32_32x32x16_bf16 v[82:97], v[106:109], v[102:105], v[82:97]
	ds_read_b128 v[106:109], v0 offset:12992
	s_waitcnt lgkmcnt(0)
	v_mfma_f32_32x32x16_bf16 v[66:81], v[106:109], v[102:105], v[66:81]
	ds_read_b128 v[102:105], v0 offset:224
	s_waitcnt lgkmcnt(0)
	v_mfma_f32_32x32x16_bf16 v[82:97], v[102:105], v[98:101], v[82:97]
	ds_read_b128 v[102:105], v0 offset:13024
	s_waitcnt lgkmcnt(0)
	v_mfma_f32_32x32x16_bf16 v[66:81], v[102:105], v[98:101], v[66:81]
	ds_read_b128 v[98:101], v0 offset:256
	s_waitcnt lgkmcnt(0)
	v_mfma_f32_32x32x16_bf16 v[82:97], v[98:101], v[134:137], v[82:97]
	ds_read_b128 v[98:101], v0 offset:13056
	s_waitcnt lgkmcnt(0)
	v_mfma_f32_32x32x16_bf16 v[66:81], v[98:101], v[134:137], v[66:81]
	ds_read_b128 v[98:101], v0 offset:288
	s_waitcnt lgkmcnt(0)
	v_mfma_f32_32x32x16_bf16 v[82:97], v[98:101], v[130:133], v[82:97]
	ds_read_b128 v[98:101], v0 offset:13088
	s_waitcnt lgkmcnt(0)
	v_mfma_f32_32x32x16_bf16 v[66:81], v[98:101], v[130:133], v[66:81]
	ds_read_b128 v[98:101], v0 offset:320
	s_waitcnt lgkmcnt(0)
	v_mfma_f32_32x32x16_bf16 v[82:97], v[98:101], v[142:145], v[82:97]
	ds_read_b128 v[98:101], v0 offset:13120
	s_waitcnt lgkmcnt(0)
	v_mfma_f32_32x32x16_bf16 v[66:81], v[98:101], v[142:145], v[66:81]
	ds_read_b128 v[98:101], v0 offset:13152
	s_waitcnt lgkmcnt(0)
	v_mfma_f32_32x32x16_bf16 v[66:81], v[98:101], v[138:141], v[66:81]
	ds_read_b128 v[98:101], v0 offset:352
	s_waitcnt lgkmcnt(0)
	v_mfma_f32_32x32x16_bf16 v[82:97], v[98:101], v[138:141], v[82:97]
	s_nop 8
	s_nop 1
	s_nop 0
	v_max_f32_e32 v0, v83, v67
	v_max_f32_e32 v98, v84, v68
	v_max3_f32 v0, v82, v66, v0
	v_max_f32_e32 v99, v85, v69
	v_max3_f32 v0, v0, v98, v99
	v_max_f32_e32 v98, v86, v70
	v_max_f32_e32 v99, v87, v71
	v_max3_f32 v0, v0, v98, v99
	v_max_f32_e32 v98, v88, v72
	v_max_f32_e32 v99, v89, v73
	v_max3_f32 v0, v0, v98, v99
	v_max_f32_e32 v98, v90, v74
	v_max_f32_e32 v99, v91, v75
	v_max3_f32 v0, v0, v98, v99
	v_max_f32_e32 v98, v92, v76
	v_max_f32_e32 v99, v93, v77
	v_max3_f32 v0, v0, v98, v99
	v_max_f32_e32 v98, v94, v78
	v_max_f32_e32 v99, v95, v79
	v_max3_f32 v0, v0, v98, v99
	v_max_f32_e32 v98, v96, v80
	v_max_f32_e32 v100, v97, v97
	v_max_f32_e32 v99, v100, v81
	v_max3_f32 v0, v0, v98, v99
	v_mov_b32_e32 v98, v0
	s_nop 1
	v_permlane32_swap_b32_e32 v0, v98
	v_max3_f32 v101, v223, v0, v98
	v_sub_f32_e32 v0, v223, v101
	v_mul_f32_e32 v0, 0x3dd53b94, v0
	v_exp_f32_e32 v98, v0
	s_nop 0
	v_cmp_eq_f32_e32 vcc, 1.0, v98
	s_cmp_eq_u64 vcc, exec
	s_cbranch_scc1 .LBB0_468
	v_pk_mul_f32 v[64:65], v[64:65], v[98:99] op_sel_hi:[1,0]
	v_pk_mul_f32 v[62:63], v[62:63], v[98:99] op_sel_hi:[1,0]
	v_pk_mul_f32 v[60:61], v[60:61], v[98:99] op_sel_hi:[1,0]
	v_pk_mul_f32 v[58:59], v[58:59], v[98:99] op_sel_hi:[1,0]
	v_pk_mul_f32 v[56:57], v[56:57], v[98:99] op_sel_hi:[1,0]
	v_pk_mul_f32 v[54:55], v[54:55], v[98:99] op_sel_hi:[1,0]
	v_pk_mul_f32 v[52:53], v[52:53], v[98:99] op_sel_hi:[1,0]
	v_pk_mul_f32 v[50:51], v[50:51], v[98:99] op_sel_hi:[1,0]
	v_pk_mul_f32 v[48:49], v[48:49], v[98:99] op_sel_hi:[1,0]
	v_pk_mul_f32 v[46:47], v[46:47], v[98:99] op_sel_hi:[1,0]
	v_pk_mul_f32 v[44:45], v[44:45], v[98:99] op_sel_hi:[1,0]
	v_pk_mul_f32 v[42:43], v[42:43], v[98:99] op_sel_hi:[1,0]
	v_pk_mul_f32 v[40:41], v[40:41], v[98:99] op_sel_hi:[1,0]
	v_pk_mul_f32 v[38:39], v[38:39], v[98:99] op_sel_hi:[1,0]
	v_pk_mul_f32 v[36:37], v[36:37], v[98:99] op_sel_hi:[1,0]
	v_pk_mul_f32 v[34:35], v[34:35], v[98:99] op_sel_hi:[1,0]
	v_pk_mul_f32 v[32:33], v[32:33], v[98:99] op_sel_hi:[1,0]
	v_pk_mul_f32 v[30:31], v[30:31], v[98:99] op_sel_hi:[1,0]
	v_pk_mul_f32 v[28:29], v[28:29], v[98:99] op_sel_hi:[1,0]
	v_pk_mul_f32 v[26:27], v[26:27], v[98:99] op_sel_hi:[1,0]
	v_pk_mul_f32 v[24:25], v[24:25], v[98:99] op_sel_hi:[1,0]
	v_pk_mul_f32 v[22:23], v[22:23], v[98:99] op_sel_hi:[1,0]
	v_pk_mul_f32 v[20:21], v[20:21], v[98:99] op_sel_hi:[1,0]
	v_pk_mul_f32 v[18:19], v[18:19], v[98:99] op_sel_hi:[1,0]
	v_pk_mul_f32 v[16:17], v[16:17], v[98:99] op_sel_hi:[1,0]
	v_pk_mul_f32 v[14:15], v[14:15], v[98:99] op_sel_hi:[1,0]
	v_pk_mul_f32 v[12:13], v[12:13], v[98:99] op_sel_hi:[1,0]
	v_pk_mul_f32 v[10:11], v[10:11], v[98:99] op_sel_hi:[1,0]
	v_pk_mul_f32 v[8:9], v[8:9], v[98:99] op_sel_hi:[1,0]
	v_pk_mul_f32 v[6:7], v[6:7], v[98:99] op_sel_hi:[1,0]
	v_pk_mul_f32 v[4:5], v[4:5], v[98:99] op_sel_hi:[1,0]
	v_pk_mul_f32 v[2:3], v[2:3], v[98:99] op_sel_hi:[1,0]
	s_branch .LBB0_468

.LBB0_783:
	s_and_b32 s36, s33, 1
	s_mul_i32 s37, s36, 0x6800
	s_add_i32 s37, s37, 0
	v_add3_u32 v0, s37, v215, v212
	ds_read_b128 v[2:5], v0
	ds_read_b128 v[6:9], v0 offset:32
	s_waitcnt lgkmcnt(1)
	v_mfma_f32_32x32x16_bf16 v[96:111], v[2:5], v[116:119], 0
	ds_read_b128 v[2:5], v0 offset:4608
	ds_read_b128 v[10:13], v0 offset:4640
	s_waitcnt lgkmcnt(1)
	v_mfma_f32_32x32x16_bf16 v[80:95], v[2:5], v[116:119], 0
	ds_read_b128 v[2:5], v0 offset:64
	ds_read_b128 v[146:149], v0 offset:96
	v_mfma_f32_32x32x16_bf16 v[96:111], v[6:9], v[112:115], v[96:111]
	s_waitcnt lgkmcnt(2)
	v_mfma_f32_32x32x16_bf16 v[80:95], v[10:13], v[112:115], v[80:95]
	s_waitcnt lgkmcnt(1)
	v_mfma_f32_32x32x16_bf16 v[96:111], v[2:5], v[124:127], v[96:111]
	ds_read_b128 v[2:5], v0 offset:4672
	ds_read_b128 v[6:9], v0 offset:4704
	v_mov_b32_e32 v0, v137
	s_waitcnt lgkmcnt(1)
	v_mfma_f32_32x32x16_bf16 v[80:95], v[2:5], v[124:127], v[80:95]
	v_lshl_add_u64 v[2:3], v[138:139], 0, s[6:7]
	v_lshl_add_u64 v[4:5], v[140:141], 0, s[6:7]
	global_load_dwordx4 v[10:13], v[2:3], off
	s_waitcnt lgkmcnt(0)
	v_mfma_f32_32x32x16_bf16 v[80:95], v[6:9], v[120:123], v[80:95]
	global_load_dwordx4 v[6:9], v[4:5], off offset:-16
	s_nop 0
	global_load_dwordx4 v[2:5], v[4:5], off
	v_mfma_f32_32x32x16_bf16 v[96:111], v[146:149], v[120:123], v[96:111]
	s_nop 7
	s_nop 2
	s_nop 0
	v_max_f32_e32 v14, v97, v81
	v_max_f32_e32 v15, v98, v82
	v_max3_f32 v14, v96, v80, v14
	v_max_f32_e32 v136, v99, v83
	v_max3_f32 v14, v14, v15, v136
	v_max_f32_e32 v15, v100, v84
	v_max_f32_e32 v136, v101, v85
	v_max3_f32 v14, v14, v15, v136
	v_max_f32_e32 v15, v102, v86
	v_max_f32_e32 v136, v103, v87
	v_max3_f32 v14, v14, v15, v136
	v_max_f32_e32 v15, v104, v88
	v_max_f32_e32 v136, v105, v89
	v_max3_f32 v14, v14, v15, v136
	v_max_f32_e32 v15, v106, v90
	v_max_f32_e32 v136, v107, v91
	v_max3_f32 v14, v14, v15, v136
	v_max_f32_e32 v15, v108, v92
	v_max_f32_e32 v136, v109, v93
	v_max3_f32 v14, v14, v15, v136
	v_max_f32_e32 v15, v110, v94
	v_max_f32_e32 v136, v111, v95
	v_max3_f32 v14, v14, v15, v136
	v_mov_b32_e32 v15, v14
	s_nop 1
	v_permlane32_swap_b32_e32 v14, v15
	v_max3_f32 v137, v0, v14, v15
	v_sub_f32_e32 v0, v0, v137
	v_mul_f32_e32 v0, 0x3e38aa3b, v0
	v_exp_f32_e32 v14, v0
	s_nop 0
	v_cmp_eq_f32_e32 vcc, 1.0, v14
	s_cmp_eq_u64 vcc, exec
	s_cbranch_scc1 .LBB0_785
	v_pk_mul_f32 v[78:79], v[78:79], v[14:15] op_sel_hi:[1,0]
	v_pk_mul_f32 v[76:77], v[76:77], v[14:15] op_sel_hi:[1,0]
	v_pk_mul_f32 v[74:75], v[74:75], v[14:15] op_sel_hi:[1,0]
	v_pk_mul_f32 v[72:73], v[72:73], v[14:15] op_sel_hi:[1,0]
	v_pk_mul_f32 v[70:71], v[70:71], v[14:15] op_sel_hi:[1,0]
	v_pk_mul_f32 v[68:69], v[68:69], v[14:15] op_sel_hi:[1,0]
	v_pk_mul_f32 v[66:67], v[66:67], v[14:15] op_sel_hi:[1,0]
	v_pk_mul_f32 v[64:65], v[64:65], v[14:15] op_sel_hi:[1,0]
	v_pk_mul_f32 v[62:63], v[62:63], v[14:15] op_sel_hi:[1,0]
	v_pk_mul_f32 v[60:61], v[60:61], v[14:15] op_sel_hi:[1,0]
	v_pk_mul_f32 v[58:59], v[58:59], v[14:15] op_sel_hi:[1,0]
	v_pk_mul_f32 v[56:57], v[56:57], v[14:15] op_sel_hi:[1,0]
	v_pk_mul_f32 v[54:55], v[54:55], v[14:15] op_sel_hi:[1,0]
	v_pk_mul_f32 v[52:53], v[52:53], v[14:15] op_sel_hi:[1,0]
	v_pk_mul_f32 v[50:51], v[50:51], v[14:15] op_sel_hi:[1,0]
	v_pk_mul_f32 v[48:49], v[48:49], v[14:15] op_sel_hi:[1,0]
	v_pk_mul_f32 v[46:47], v[46:47], v[14:15] op_sel_hi:[1,0]
	v_pk_mul_f32 v[44:45], v[44:45], v[14:15] op_sel_hi:[1,0]
	v_pk_mul_f32 v[42:43], v[42:43], v[14:15] op_sel_hi:[1,0]
	v_pk_mul_f32 v[40:41], v[40:41], v[14:15] op_sel_hi:[1,0]
	v_pk_mul_f32 v[38:39], v[38:39], v[14:15] op_sel_hi:[1,0]
	v_pk_mul_f32 v[36:37], v[36:37], v[14:15] op_sel_hi:[1,0]
	v_pk_mul_f32 v[34:35], v[34:35], v[14:15] op_sel_hi:[1,0]
	v_pk_mul_f32 v[32:33], v[32:33], v[14:15] op_sel_hi:[1,0]
	v_pk_mul_f32 v[30:31], v[30:31], v[14:15] op_sel_hi:[1,0]
	v_pk_mul_f32 v[28:29], v[28:29], v[14:15] op_sel_hi:[1,0]
	v_pk_mul_f32 v[26:27], v[26:27], v[14:15] op_sel_hi:[1,0]
	v_pk_mul_f32 v[24:25], v[24:25], v[14:15] op_sel_hi:[1,0]
	v_pk_mul_f32 v[22:23], v[22:23], v[14:15] op_sel_hi:[1,0]
	v_pk_mul_f32 v[20:21], v[20:21], v[14:15] op_sel_hi:[1,0]
	v_pk_mul_f32 v[18:19], v[18:19], v[14:15] op_sel_hi:[1,0]
	v_pk_mul_f32 v[16:17], v[16:17], v[14:15] op_sel_hi:[1,0]

.LBB0_787:
	s_bitcmp1_b32 s35, 0
	s_cselect_b32 s6, 0x6800, 0
	s_add_i32 s6, s6, 0
	v_add3_u32 v0, s6, v215, v212
	ds_read_b128 v[2:5], v0
	s_waitcnt lgkmcnt(0)
	v_mfma_f32_32x32x16_bf16 v[80:95], v[2:5], v[116:119], 0
	ds_read_b128 v[2:5], v0 offset:4608
	s_waitcnt lgkmcnt(0)
	v_mfma_f32_32x32x16_bf16 v[96:111], v[2:5], v[116:119], 0
	ds_read_b128 v[2:5], v0 offset:32
	s_waitcnt lgkmcnt(0)
	v_mfma_f32_32x32x16_bf16 v[80:95], v[2:5], v[112:115], v[80:95]
	ds_read_b128 v[2:5], v0 offset:4640
	s_waitcnt lgkmcnt(0)
	v_mfma_f32_32x32x16_bf16 v[96:111], v[2:5], v[112:115], v[96:111]
	ds_read_b128 v[2:5], v0 offset:64
	s_waitcnt lgkmcnt(0)
	v_mfma_f32_32x32x16_bf16 v[80:95], v[2:5], v[124:127], v[80:95]
	ds_read_b128 v[2:5], v0 offset:4672
	s_waitcnt lgkmcnt(0)
	v_mfma_f32_32x32x16_bf16 v[96:111], v[2:5], v[124:127], v[96:111]
	ds_read_b128 v[2:5], v0 offset:4704
	s_waitcnt lgkmcnt(0)
	v_mfma_f32_32x32x16_bf16 v[96:111], v[2:5], v[120:123], v[96:111]
	ds_read_b128 v[2:5], v0 offset:96
	s_waitcnt lgkmcnt(0)
	v_mfma_f32_32x32x16_bf16 v[80:95], v[2:5], v[120:123], v[80:95]
	s_nop 8
	s_nop 1
	s_nop 0
	v_max_f32_e32 v0, v81, v97
	v_max_f32_e32 v2, v82, v98
	v_max3_f32 v0, v80, v96, v0
	v_max_f32_e32 v3, v83, v99
	v_max3_f32 v0, v0, v2, v3
	v_max_f32_e32 v2, v84, v100
	v_max_f32_e32 v3, v85, v101
	v_max3_f32 v0, v0, v2, v3
	v_max_f32_e32 v2, v86, v102
	v_max_f32_e32 v3, v87, v103
	v_max3_f32 v0, v0, v2, v3
	v_max_f32_e32 v2, v88, v104
	v_max_f32_e32 v3, v89, v105
	v_max3_f32 v0, v0, v2, v3
	v_max_f32_e32 v2, v90, v106
	v_max_f32_e32 v3, v91, v107
	v_max3_f32 v0, v0, v2, v3
	v_max_f32_e32 v2, v92, v108
	v_max_f32_e32 v3, v93, v109
	v_max3_f32 v0, v0, v2, v3
	v_max_f32_e32 v2, v94, v110
	v_max_f32_e32 v4, v95, v95
	v_max_f32_e32 v3, v4, v111
	v_max3_f32 v0, v0, v2, v3
	v_mov_b32_e32 v2, v0
	s_nop 1
	v_permlane32_swap_b32_e32 v0, v2
	v_max3_f32 v3, v137, v0, v2
	v_sub_f32_e32 v0, v137, v3
	v_mul_f32_e32 v0, 0x3e38aa3b, v0
	v_exp_f32_e32 v0, v0
	s_nop 0
	v_cmp_eq_f32_e32 vcc, 1.0, v0
	s_cmp_eq_u64 vcc, exec
	s_cbranch_scc1 .LBB0_789
	v_pk_mul_f32 v[78:79], v[78:79], v[0:1] op_sel_hi:[1,0]
	v_pk_mul_f32 v[76:77], v[76:77], v[0:1] op_sel_hi:[1,0]
	v_pk_mul_f32 v[74:75], v[74:75], v[0:1] op_sel_hi:[1,0]
	v_pk_mul_f32 v[72:73], v[72:73], v[0:1] op_sel_hi:[1,0]
	v_pk_mul_f32 v[70:71], v[70:71], v[0:1] op_sel_hi:[1,0]
	v_pk_mul_f32 v[68:69], v[68:69], v[0:1] op_sel_hi:[1,0]
	v_pk_mul_f32 v[66:67], v[66:67], v[0:1] op_sel_hi:[1,0]
	v_pk_mul_f32 v[64:65], v[64:65], v[0:1] op_sel_hi:[1,0]
	v_pk_mul_f32 v[62:63], v[62:63], v[0:1] op_sel_hi:[1,0]
	v_pk_mul_f32 v[60:61], v[60:61], v[0:1] op_sel_hi:[1,0]
	v_pk_mul_f32 v[58:59], v[58:59], v[0:1] op_sel_hi:[1,0]
	v_pk_mul_f32 v[56:57], v[56:57], v[0:1] op_sel_hi:[1,0]
	v_pk_mul_f32 v[54:55], v[54:55], v[0:1] op_sel_hi:[1,0]
	v_pk_mul_f32 v[52:53], v[52:53], v[0:1] op_sel_hi:[1,0]
	v_pk_mul_f32 v[50:51], v[50:51], v[0:1] op_sel_hi:[1,0]
	v_pk_mul_f32 v[48:49], v[48:49], v[0:1] op_sel_hi:[1,0]
	v_pk_mul_f32 v[46:47], v[46:47], v[0:1] op_sel_hi:[1,0]
	v_pk_mul_f32 v[44:45], v[44:45], v[0:1] op_sel_hi:[1,0]
	v_pk_mul_f32 v[42:43], v[42:43], v[0:1] op_sel_hi:[1,0]
	v_pk_mul_f32 v[40:41], v[40:41], v[0:1] op_sel_hi:[1,0]
	v_pk_mul_f32 v[38:39], v[38:39], v[0:1] op_sel_hi:[1,0]
	v_pk_mul_f32 v[36:37], v[36:37], v[0:1] op_sel_hi:[1,0]
	v_pk_mul_f32 v[34:35], v[34:35], v[0:1] op_sel_hi:[1,0]
	v_pk_mul_f32 v[32:33], v[32:33], v[0:1] op_sel_hi:[1,0]
	v_pk_mul_f32 v[30:31], v[30:31], v[0:1] op_sel_hi:[1,0]
	v_pk_mul_f32 v[28:29], v[28:29], v[0:1] op_sel_hi:[1,0]
	v_pk_mul_f32 v[26:27], v[26:27], v[0:1] op_sel_hi:[1,0]
	v_pk_mul_f32 v[24:25], v[24:25], v[0:1] op_sel_hi:[1,0]
	v_pk_mul_f32 v[22:23], v[22:23], v[0:1] op_sel_hi:[1,0]
	v_pk_mul_f32 v[20:21], v[20:21], v[0:1] op_sel_hi:[1,0]
	v_pk_mul_f32 v[18:19], v[18:19], v[0:1] op_sel_hi:[1,0]
	v_pk_mul_f32 v[16:17], v[16:17], v[0:1] op_sel_hi:[1,0]

.LBB0_808:
	s_and_b32 s10, s7, 1
	s_mul_i32 s11, s10, 0x8800
	s_add_i32 s11, s11, 0
	v_add3_u32 v0, s11, v211, v212
	ds_read_b128 v[66:69], v0
	ds_read_b128 v[130:133], v0 offset:32
	s_waitcnt lgkmcnt(1)
	v_mfma_f32_32x32x16_bf16 v[82:97], v[66:69], v[126:129], 0
	ds_read_b128 v[66:69], v0 offset:8704
	ds_read_b128 v[134:137], v0 offset:8736
	s_waitcnt lgkmcnt(1)
	v_mfma_f32_32x32x16_bf16 v[66:81], v[66:69], v[126:129], 0
	v_mfma_f32_32x32x16_bf16 v[82:97], v[130:133], v[118:121], v[82:97]
	s_waitcnt lgkmcnt(0)
	v_mfma_f32_32x32x16_bf16 v[66:81], v[134:137], v[118:121], v[66:81]
	ds_read_b128 v[130:133], v0 offset:64
	ds_read_b128 v[134:137], v0 offset:96
	s_waitcnt lgkmcnt(1)
	v_mfma_f32_32x32x16_bf16 v[82:97], v[130:133], v[122:125], v[82:97]
	ds_read_b128 v[130:133], v0 offset:8768
	ds_read_b128 v[138:141], v0 offset:8800
	s_waitcnt lgkmcnt(1)
	v_mfma_f32_32x32x16_bf16 v[66:81], v[130:133], v[122:125], v[66:81]
	v_mfma_f32_32x32x16_bf16 v[82:97], v[134:137], v[114:117], v[82:97]
	ds_read_b128 v[130:133], v0 offset:128
	ds_read_b128 v[134:137], v0 offset:160
	s_waitcnt lgkmcnt(2)
	v_mfma_f32_32x32x16_bf16 v[66:81], v[138:141], v[114:117], v[66:81]
	s_waitcnt lgkmcnt(1)
	v_mfma_f32_32x32x16_bf16 v[82:97], v[130:133], v[106:109], v[82:97]
	ds_read_b128 v[130:133], v0 offset:8832
	ds_read_b128 v[138:141], v0 offset:8864
	s_waitcnt lgkmcnt(1)
	v_mfma_f32_32x32x16_bf16 v[66:81], v[130:133], v[106:109], v[66:81]
	ds_read_b128 v[130:133], v0 offset:192
	ds_read_b128 v[158:161], v0 offset:224
	v_mfma_f32_32x32x16_bf16 v[82:97], v[134:137], v[110:113], v[82:97]
	s_waitcnt lgkmcnt(2)
	v_mfma_f32_32x32x16_bf16 v[66:81], v[138:141], v[110:113], v[66:81]
	v_lshl_add_u64 v[138:139], v[148:149], 0, s[2:3]
	s_waitcnt lgkmcnt(1)
	v_mfma_f32_32x32x16_bf16 v[82:97], v[130:133], v[98:101], v[82:97]
	ds_read_b128 v[130:133], v0 offset:8896
	ds_read_b128 v[134:137], v0 offset:8928
	v_mov_b32_e32 v0, v147
	s_waitcnt lgkmcnt(1)
	v_mfma_f32_32x32x16_bf16 v[66:81], v[130:133], v[98:101], v[66:81]
	v_lshl_add_u64 v[130:131], v[152:153], 0, s[2:3]
	v_lshl_add_u64 v[132:133], v[150:151], 0, s[2:3]
	global_load_dwordx4 v[142:145], v[132:133], off
	s_nop 0
	global_load_dwordx4 v[138:141], v[138:139], off
	s_waitcnt lgkmcnt(0)
	v_mfma_f32_32x32x16_bf16 v[66:81], v[134:137], v[102:105], v[66:81]
	global_load_dwordx4 v[134:137], v[130:131], off offset:-16
	s_nop 0
	global_load_dwordx4 v[130:133], v[130:131], off
	v_mfma_f32_32x32x16_bf16 v[82:97], v[158:161], v[102:105], v[82:97]
	s_nop 7
	s_nop 2
	s_nop 0
	v_max_f32_e32 v146, v83, v67
	v_max_f32_e32 v147, v84, v68
	v_max3_f32 v146, v82, v66, v146
	v_max_f32_e32 v154, v85, v69
	v_max3_f32 v146, v146, v147, v154
	v_max_f32_e32 v147, v86, v70
	v_max_f32_e32 v154, v87, v71
	v_max3_f32 v146, v146, v147, v154
	v_max_f32_e32 v147, v88, v72
	v_max_f32_e32 v154, v89, v73
	v_max3_f32 v146, v146, v147, v154
	v_max_f32_e32 v147, v90, v74
	v_max_f32_e32 v154, v91, v75
	v_max3_f32 v146, v146, v147, v154
	v_max_f32_e32 v147, v92, v76
	v_max_f32_e32 v154, v93, v77
	v_max3_f32 v146, v146, v147, v154
	v_max_f32_e32 v147, v94, v78
	v_max_f32_e32 v154, v95, v79
	v_max3_f32 v146, v146, v147, v154
	v_max_f32_e32 v147, v96, v80
	v_max_f32_e32 v157, v97, v97
	v_max_f32_e32 v154, v157, v81
	v_max3_f32 v146, v146, v147, v154
	v_mov_b32_e32 v147, v146
	s_nop 1
	v_permlane32_swap_b32_e32 v146, v147
	v_max3_f32 v147, v0, v146, v147
	v_sub_f32_e32 v0, v0, v147
	v_mul_f32_e32 v0, 0x3e0293ee, v0
	v_exp_f32_e32 v154, v0
	s_nop 0
	v_cmp_eq_f32_e32 vcc, 1.0, v154
	s_cmp_eq_u64 vcc, exec
	s_cbranch_scc1 .LBB0_810
	v_pk_mul_f32 v[64:65], v[64:65], v[154:155] op_sel_hi:[1,0]
	v_pk_mul_f32 v[62:63], v[62:63], v[154:155] op_sel_hi:[1,0]
	v_pk_mul_f32 v[60:61], v[60:61], v[154:155] op_sel_hi:[1,0]
	v_pk_mul_f32 v[58:59], v[58:59], v[154:155] op_sel_hi:[1,0]
	v_pk_mul_f32 v[56:57], v[56:57], v[154:155] op_sel_hi:[1,0]
	v_pk_mul_f32 v[54:55], v[54:55], v[154:155] op_sel_hi:[1,0]
	v_pk_mul_f32 v[52:53], v[52:53], v[154:155] op_sel_hi:[1,0]
	v_pk_mul_f32 v[50:51], v[50:51], v[154:155] op_sel_hi:[1,0]
	v_pk_mul_f32 v[48:49], v[48:49], v[154:155] op_sel_hi:[1,0]
	v_pk_mul_f32 v[46:47], v[46:47], v[154:155] op_sel_hi:[1,0]
	v_pk_mul_f32 v[44:45], v[44:45], v[154:155] op_sel_hi:[1,0]
	v_pk_mul_f32 v[42:43], v[42:43], v[154:155] op_sel_hi:[1,0]
	v_pk_mul_f32 v[40:41], v[40:41], v[154:155] op_sel_hi:[1,0]
	v_pk_mul_f32 v[38:39], v[38:39], v[154:155] op_sel_hi:[1,0]
	v_pk_mul_f32 v[36:37], v[36:37], v[154:155] op_sel_hi:[1,0]
	v_pk_mul_f32 v[34:35], v[34:35], v[154:155] op_sel_hi:[1,0]
	v_pk_mul_f32 v[32:33], v[32:33], v[154:155] op_sel_hi:[1,0]
	v_pk_mul_f32 v[30:31], v[30:31], v[154:155] op_sel_hi:[1,0]
	v_pk_mul_f32 v[28:29], v[28:29], v[154:155] op_sel_hi:[1,0]
	v_pk_mul_f32 v[26:27], v[26:27], v[154:155] op_sel_hi:[1,0]
	v_pk_mul_f32 v[24:25], v[24:25], v[154:155] op_sel_hi:[1,0]
	v_pk_mul_f32 v[22:23], v[22:23], v[154:155] op_sel_hi:[1,0]
	v_pk_mul_f32 v[20:21], v[20:21], v[154:155] op_sel_hi:[1,0]
	v_pk_mul_f32 v[18:19], v[18:19], v[154:155] op_sel_hi:[1,0]
	v_pk_mul_f32 v[16:17], v[16:17], v[154:155] op_sel_hi:[1,0]
	v_pk_mul_f32 v[14:15], v[14:15], v[154:155] op_sel_hi:[1,0]
	v_pk_mul_f32 v[12:13], v[12:13], v[154:155] op_sel_hi:[1,0]
	v_pk_mul_f32 v[10:11], v[10:11], v[154:155] op_sel_hi:[1,0]
	v_pk_mul_f32 v[8:9], v[8:9], v[154:155] op_sel_hi:[1,0]
	v_pk_mul_f32 v[6:7], v[6:7], v[154:155] op_sel_hi:[1,0]
	v_pk_mul_f32 v[4:5], v[4:5], v[154:155] op_sel_hi:[1,0]
	v_pk_mul_f32 v[2:3], v[2:3], v[154:155] op_sel_hi:[1,0]

.LBB0_812:
	s_bitcmp1_b32 s9, 0
	s_cselect_b32 s2, 0x8800, 0
	s_add_i32 s2, s2, 0
	v_add3_u32 v0, s2, v211, v212
	ds_read_b128 v[66:69], v0
	s_waitcnt lgkmcnt(0)
	v_mfma_f32_32x32x16_bf16 v[82:97], v[66:69], v[126:129], 0
	ds_read_b128 v[66:69], v0 offset:8704
	s_waitcnt lgkmcnt(0)
	v_mfma_f32_32x32x16_bf16 v[66:81], v[66:69], v[126:129], 0
	ds_read_b128 v[126:129], v0 offset:32
	s_waitcnt lgkmcnt(0)
	v_mfma_f32_32x32x16_bf16 v[82:97], v[126:129], v[118:121], v[82:97]
	ds_read_b128 v[126:129], v0 offset:8736
	s_waitcnt lgkmcnt(0)
	v_mfma_f32_32x32x16_bf16 v[66:81], v[126:129], v[118:121], v[66:81]
	ds_read_b128 v[118:121], v0 offset:64
	s_waitcnt lgkmcnt(0)
	v_mfma_f32_32x32x16_bf16 v[82:97], v[118:121], v[122:125], v[82:97]
	ds_read_b128 v[118:121], v0 offset:8768
	s_waitcnt lgkmcnt(0)
	v_mfma_f32_32x32x16_bf16 v[66:81], v[118:121], v[122:125], v[66:81]
	ds_read_b128 v[118:121], v0 offset:96
	s_waitcnt lgkmcnt(0)
	v_mfma_f32_32x32x16_bf16 v[82:97], v[118:121], v[114:117], v[82:97]
	ds_read_b128 v[118:121], v0 offset:8800
	s_waitcnt lgkmcnt(0)
	v_mfma_f32_32x32x16_bf16 v[66:81], v[118:121], v[114:117], v[66:81]
	ds_read_b128 v[114:117], v0 offset:128
	s_waitcnt lgkmcnt(0)
	v_mfma_f32_32x32x16_bf16 v[82:97], v[114:117], v[106:109], v[82:97]
	ds_read_b128 v[114:117], v0 offset:8832
	s_waitcnt lgkmcnt(0)
	v_mfma_f32_32x32x16_bf16 v[66:81], v[114:117], v[106:109], v[66:81]
	ds_read_b128 v[106:109], v0 offset:160
	s_waitcnt lgkmcnt(0)
	v_mfma_f32_32x32x16_bf16 v[82:97], v[106:109], v[110:113], v[82:97]
	ds_read_b128 v[106:109], v0 offset:8864
	s_waitcnt lgkmcnt(0)
	v_mfma_f32_32x32x16_bf16 v[66:81], v[106:109], v[110:113], v[66:81]
	ds_read_b128 v[106:109], v0 offset:192
	s_waitcnt lgkmcnt(0)
	v_mfma_f32_32x32x16_bf16 v[82:97], v[106:109], v[98:101], v[82:97]
	ds_read_b128 v[106:109], v0 offset:8896
	s_waitcnt lgkmcnt(0)
	v_mfma_f32_32x32x16_bf16 v[66:81], v[106:109], v[98:101], v[66:81]
	ds_read_b128 v[98:101], v0 offset:8928
	s_waitcnt lgkmcnt(0)
	v_mfma_f32_32x32x16_bf16 v[66:81], v[98:101], v[102:105], v[66:81]
	ds_read_b128 v[98:101], v0 offset:224
	s_waitcnt lgkmcnt(0)
	v_mfma_f32_32x32x16_bf16 v[82:97], v[98:101], v[102:105], v[82:97]
	s_nop 8
	s_nop 1
	s_nop 0
	v_max_f32_e32 v0, v83, v67
	v_max_f32_e32 v98, v84, v68
	v_max3_f32 v0, v82, v66, v0
	v_max_f32_e32 v99, v85, v69
	v_max3_f32 v0, v0, v98, v99
	v_max_f32_e32 v98, v86, v70
	v_max_f32_e32 v99, v87, v71
	v_max3_f32 v0, v0, v98, v99
	v_max_f32_e32 v98, v88, v72
	v_max_f32_e32 v99, v89, v73
	v_max3_f32 v0, v0, v98, v99
	v_max_f32_e32 v98, v90, v74
	v_max_f32_e32 v99, v91, v75
	v_max3_f32 v0, v0, v98, v99
	v_max_f32_e32 v98, v92, v76
	v_max_f32_e32 v99, v93, v77
	v_max3_f32 v0, v0, v98, v99
	v_max_f32_e32 v98, v94, v78
	v_max_f32_e32 v99, v95, v79
	v_max3_f32 v0, v0, v98, v99
	v_max_f32_e32 v98, v96, v80
	v_max_f32_e32 v100, v97, v97
	v_max_f32_e32 v99, v100, v81
	v_max3_f32 v0, v0, v98, v99
	v_mov_b32_e32 v98, v0
	s_nop 1
	v_permlane32_swap_b32_e32 v0, v98
	v_max3_f32 v101, v147, v0, v98
	v_sub_f32_e32 v0, v147, v101
	v_mul_f32_e32 v0, 0x3e0293ee, v0
	v_exp_f32_e32 v98, v0
	s_nop 0
	v_cmp_eq_f32_e32 vcc, 1.0, v98
	s_cmp_eq_u64 vcc, exec
	s_cbranch_scc1 .LBB0_814
	v_pk_mul_f32 v[64:65], v[64:65], v[98:99] op_sel_hi:[1,0]
	v_pk_mul_f32 v[62:63], v[62:63], v[98:99] op_sel_hi:[1,0]
	v_pk_mul_f32 v[60:61], v[60:61], v[98:99] op_sel_hi:[1,0]
	v_pk_mul_f32 v[58:59], v[58:59], v[98:99] op_sel_hi:[1,0]
	v_pk_mul_f32 v[56:57], v[56:57], v[98:99] op_sel_hi:[1,0]
	v_pk_mul_f32 v[54:55], v[54:55], v[98:99] op_sel_hi:[1,0]
	v_pk_mul_f32 v[52:53], v[52:53], v[98:99] op_sel_hi:[1,0]
	v_pk_mul_f32 v[50:51], v[50:51], v[98:99] op_sel_hi:[1,0]
	v_pk_mul_f32 v[48:49], v[48:49], v[98:99] op_sel_hi:[1,0]
	v_pk_mul_f32 v[46:47], v[46:47], v[98:99] op_sel_hi:[1,0]
	v_pk_mul_f32 v[44:45], v[44:45], v[98:99] op_sel_hi:[1,0]
	v_pk_mul_f32 v[42:43], v[42:43], v[98:99] op_sel_hi:[1,0]
	v_pk_mul_f32 v[40:41], v[40:41], v[98:99] op_sel_hi:[1,0]
	v_pk_mul_f32 v[38:39], v[38:39], v[98:99] op_sel_hi:[1,0]
	v_pk_mul_f32 v[36:37], v[36:37], v[98:99] op_sel_hi:[1,0]
	v_pk_mul_f32 v[34:35], v[34:35], v[98:99] op_sel_hi:[1,0]
	v_pk_mul_f32 v[32:33], v[32:33], v[98:99] op_sel_hi:[1,0]
	v_pk_mul_f32 v[30:31], v[30:31], v[98:99] op_sel_hi:[1,0]
	v_pk_mul_f32 v[28:29], v[28:29], v[98:99] op_sel_hi:[1,0]
	v_pk_mul_f32 v[26:27], v[26:27], v[98:99] op_sel_hi:[1,0]
	v_pk_mul_f32 v[24:25], v[24:25], v[98:99] op_sel_hi:[1,0]
	v_pk_mul_f32 v[22:23], v[22:23], v[98:99] op_sel_hi:[1,0]
	v_pk_mul_f32 v[20:21], v[20:21], v[98:99] op_sel_hi:[1,0]
	v_pk_mul_f32 v[18:19], v[18:19], v[98:99] op_sel_hi:[1,0]
	v_pk_mul_f32 v[16:17], v[16:17], v[98:99] op_sel_hi:[1,0]
	v_pk_mul_f32 v[14:15], v[14:15], v[98:99] op_sel_hi:[1,0]
	v_pk_mul_f32 v[12:13], v[12:13], v[98:99] op_sel_hi:[1,0]
	v_pk_mul_f32 v[10:11], v[10:11], v[98:99] op_sel_hi:[1,0]
	v_pk_mul_f32 v[8:9], v[8:9], v[98:99] op_sel_hi:[1,0]
	v_pk_mul_f32 v[6:7], v[6:7], v[98:99] op_sel_hi:[1,0]
	v_pk_mul_f32 v[4:5], v[4:5], v[98:99] op_sel_hi:[1,0]
	v_pk_mul_f32 v[2:3], v[2:3], v[98:99] op_sel_hi:[1,0]
